# p6last + second half of the P7 final out stores written through (smaller end-of-kernel L2 flush)
# speedup vs baseline: 1.0047x; 1.0047x over previous
; __device__ __forceinline__ void st_bf16x8(bf16_t* p, const f32x4 a, const f32x4 b) { uint4 o; o.x = cvt_pk_bf16(a[0], a[1]); o.y = cvt_pk_bf16(a[2], a[3]); o.z = cvt_pk_bf16(b[0], b[1]); o.w = cvt_pk_bf16(b[2], b[3]); *(uint4*)p = o; }
;     __device__ __forceinline__ void fused(f32x4 (&acc)[2][2][4][2], const Unit& u, int wr, int wc, int fr, int fq, float* smem) const {
;     ...
;         __syncthreads();
; #pragma unroll
;         for (int ai = 0; ai < 2; ++ai)
; #pragma unroll
;             for (int m = 0; m < 4; ++m) { const int rl = rl0 + ai * HALF + m * 16; const size_t ro = (size_t)(u.pm * BM + rl) * DM; const float r = rsv[rl];
; #pragma unroll
;                 for (int bj = 0; bj < 2; ++bj) { const int c = cb + bj * HALF; const f32x4 v0 = acc[ai][bj][m][0], v1 = acc[ai][bj][m][1];
;                     if (MODE == 0) { st_bf16x8(X1 + ro + c, v0, v1); st_bf16x8(H + ro + c, v0 * r * gs[bj][0] + sh[bj][0], v1 * r * gs[bj][1] + sh[bj][1]); }
;                     else { *(f32x4*)(out + ro + c) = v0 * r * gs[bj][0]; *(f32x4*)(out + ro + c + 4) = v1 * r * gs[bj][1]; } } }
.LBB0_817:
	s_or_b64 exec, exec, s[4:5]
	v_lshl_add_u32 v80, v184, 2, 16
	v_add_u32_e32 v128, 0x1000, v80
	s_waitcnt lgkmcnt(0)
	s_barrier
	ds_read2_b32 v[186:187], v128 offset1:16
	ds_read2_b32 v[188:189], v128 offset0:32 offset1:48
	ds_read2_b32 v[190:191], v128 offset0:128 offset1:144
	ds_read2_b32 v[192:193], v128 offset0:160 offset1:176
	v_and_b32_e32 v142, 1, v168
	v_and_b32_e32 v196, -2, v168
	v_mov_b32_e32 v197, v169
	v_lshlrev_b64 v[140:141], 12, v[196:197]
	v_lshl_add_u64 v[140:141], s[56:57], 0, v[140:141]
	v_lshlrev_b64 v[194:195], 2, v[170:171]
	v_lshl_add_u64 v[140:141], v[140:141], 0, v[194:195]
	v_lshlrev_b32_e32 v142, 4, v142
	v_add_u32_e32 v142, 0x800, v142
	v_mov_b32_e32 v143, 0
	v_lshl_add_u64 v[140:141], v[140:141], 0, v[142:143]
	s_mov_b32 s8, 0x55555555
	s_mov_b32 s9, 0x55555555
	s_mov_b32 s10, 0xaaaaaaaa
	s_mov_b32 s11, 0xaaaaaaaa
	s_mov_b64 s[12:13], 0x10000
	s_mov_b64 s[14:15], 0x50000
	v_mov_b32_e32 v199, 0
	s_waitcnt vmcnt(0) lgkmcnt(0)
	v_mov_b32_e32 v198, v186
	v_pk_mul_f32 v[124:125], v[124:125], v[198:199] op_sel_hi:[1,0]
	v_pk_mul_f32 v[126:127], v[126:127], v[198:199] op_sel_hi:[1,0]
	v_pk_mul_f32 v[120:121], v[120:121], v[198:199] op_sel_hi:[1,0]
	v_pk_mul_f32 v[122:123], v[122:123], v[198:199] op_sel_hi:[1,0]
	v_pk_mul_f32 v[124:125], v[12:13], v[124:125]
	v_pk_mul_f32 v[126:127], v[14:15], v[126:127]
	v_pk_mul_f32 v[120:121], v[8:9], v[120:121]
	v_pk_mul_f32 v[122:123], v[10:11], v[122:123]
	s_mov_b64 vcc, s[8:9]
	s_nop 0
	v_cndmask_b32_dpp v132, v120, v124, vcc quad_perm:[1,0,3,2] row_mask:0xf bank_mask:0xf
	v_cndmask_b32_dpp v133, v121, v125, vcc quad_perm:[1,0,3,2] row_mask:0xf bank_mask:0xf
	v_cndmask_b32_dpp v134, v122, v126, vcc quad_perm:[1,0,3,2] row_mask:0xf bank_mask:0xf
	v_cndmask_b32_dpp v135, v123, v127, vcc quad_perm:[1,0,3,2] row_mask:0xf bank_mask:0xf
	s_mov_b64 vcc, s[10:11]
	v_cndmask_b32_dpp v136, v124, v120, vcc quad_perm:[1,0,3,2] row_mask:0xf bank_mask:0xf
	v_cndmask_b32_dpp v137, v125, v121, vcc quad_perm:[1,0,3,2] row_mask:0xf bank_mask:0xf
	v_cndmask_b32_dpp v138, v126, v122, vcc quad_perm:[1,0,3,2] row_mask:0xf bank_mask:0xf
	v_cndmask_b32_dpp v139, v127, v123, vcc quad_perm:[1,0,3,2] row_mask:0xf bank_mask:0xf
	global_store_dwordx4 v[140:141], v[132:135], off offset:-2048
	global_store_dwordx4 v[140:141], v[136:139], off offset:2048
	v_pk_mul_f32 v[116:117], v[116:117], v[198:199] op_sel_hi:[1,0]
	v_pk_mul_f32 v[118:119], v[118:119], v[198:199] op_sel_hi:[1,0]
	v_pk_mul_f32 v[112:113], v[112:113], v[198:199] op_sel_hi:[1,0]
	v_pk_mul_f32 v[114:115], v[114:115], v[198:199] op_sel_hi:[1,0]
	v_pk_mul_f32 v[116:117], v[4:5], v[116:117]
	v_pk_mul_f32 v[118:119], v[6:7], v[118:119]
	v_pk_mul_f32 v[112:113], v[0:1], v[112:113]
	v_pk_mul_f32 v[114:115], v[2:3], v[114:115]
	s_mov_b64 vcc, s[8:9]
	s_nop 0
	v_cndmask_b32_dpp v132, v112, v116, vcc quad_perm:[1,0,3,2] row_mask:0xf bank_mask:0xf
	v_cndmask_b32_dpp v133, v113, v117, vcc quad_perm:[1,0,3,2] row_mask:0xf bank_mask:0xf
	v_cndmask_b32_dpp v134, v114, v118, vcc quad_perm:[1,0,3,2] row_mask:0xf bank_mask:0xf
	v_cndmask_b32_dpp v135, v115, v119, vcc quad_perm:[1,0,3,2] row_mask:0xf bank_mask:0xf
	s_mov_b64 vcc, s[10:11]
	v_cndmask_b32_dpp v136, v116, v112, vcc quad_perm:[1,0,3,2] row_mask:0xf bank_mask:0xf
	v_cndmask_b32_dpp v137, v117, v113, vcc quad_perm:[1,0,3,2] row_mask:0xf bank_mask:0xf
	v_cndmask_b32_dpp v138, v118, v114, vcc quad_perm:[1,0,3,2] row_mask:0xf bank_mask:0xf
	v_cndmask_b32_dpp v139, v119, v115, vcc quad_perm:[1,0,3,2] row_mask:0xf bank_mask:0xf
	global_store_dwordx4 v[140:141], v[132:135], off offset:-1536
	global_store_dwordx4 v[140:141], v[136:139], off offset:2560
	v_lshl_add_u64 v[140:141], v[140:141], 0, s[12:13]
	v_mov_b32_e32 v198, v187
	v_pk_mul_f32 v[108:109], v[108:109], v[198:199] op_sel_hi:[1,0]
	v_pk_mul_f32 v[110:111], v[110:111], v[198:199] op_sel_hi:[1,0]
	v_pk_mul_f32 v[104:105], v[104:105], v[198:199] op_sel_hi:[1,0]
	v_pk_mul_f32 v[106:107], v[106:107], v[198:199] op_sel_hi:[1,0]
	v_pk_mul_f32 v[108:109], v[12:13], v[108:109]
	v_pk_mul_f32 v[110:111], v[14:15], v[110:111]
	v_pk_mul_f32 v[104:105], v[8:9], v[104:105]
	v_pk_mul_f32 v[106:107], v[10:11], v[106:107]
	s_mov_b64 vcc, s[8:9]
	s_nop 0
	v_cndmask_b32_dpp v132, v104, v108, vcc quad_perm:[1,0,3,2] row_mask:0xf bank_mask:0xf
	v_cndmask_b32_dpp v133, v105, v109, vcc quad_perm:[1,0,3,2] row_mask:0xf bank_mask:0xf
	v_cndmask_b32_dpp v134, v106, v110, vcc quad_perm:[1,0,3,2] row_mask:0xf bank_mask:0xf
	v_cndmask_b32_dpp v135, v107, v111, vcc quad_perm:[1,0,3,2] row_mask:0xf bank_mask:0xf
	s_mov_b64 vcc, s[10:11]
	v_cndmask_b32_dpp v136, v108, v104, vcc quad_perm:[1,0,3,2] row_mask:0xf bank_mask:0xf
	v_cndmask_b32_dpp v137, v109, v105, vcc quad_perm:[1,0,3,2] row_mask:0xf bank_mask:0xf
	v_cndmask_b32_dpp v138, v110, v106, vcc quad_perm:[1,0,3,2] row_mask:0xf bank_mask:0xf
	v_cndmask_b32_dpp v139, v111, v107, vcc quad_perm:[1,0,3,2] row_mask:0xf bank_mask:0xf
	global_store_dwordx4 v[140:141], v[132:135], off offset:-2048
	global_store_dwordx4 v[140:141], v[136:139], off offset:2048
	v_pk_mul_f32 v[100:101], v[100:101], v[198:199] op_sel_hi:[1,0]
	v_pk_mul_f32 v[102:103], v[102:103], v[198:199] op_sel_hi:[1,0]
	v_pk_mul_f32 v[96:97], v[96:97], v[198:199] op_sel_hi:[1,0]
	v_pk_mul_f32 v[98:99], v[98:99], v[198:199] op_sel_hi:[1,0]
	v_pk_mul_f32 v[100:101], v[4:5], v[100:101]
	v_pk_mul_f32 v[102:103], v[6:7], v[102:103]
	v_pk_mul_f32 v[96:97], v[0:1], v[96:97]
	v_pk_mul_f32 v[98:99], v[2:3], v[98:99]
	s_mov_b64 vcc, s[8:9]
	s_nop 0
	v_cndmask_b32_dpp v132, v96, v100, vcc quad_perm:[1,0,3,2] row_mask:0xf bank_mask:0xf
; __device__ __forceinline__ void st_bf16x8(bf16_t* p, const f32x4 a, const f32x4 b) { uint4 o; o.x = cvt_pk_bf16(a[0], a[1]); o.y = cvt_pk_bf16(a[2], a[3]); o.z = cvt_pk_bf16(b[0], b[1]); o.w = cvt_pk_bf16(b[2], b[3]); *(uint4*)p = o; }
;     __device__ __forceinline__ void fused(f32x4 (&acc)[2][2][4][2], const Unit& u, int wr, int wc, int fr, int fq, float* smem) const {
;     ...
;         for (int ai = 0; ai < 2; ++ai)
; #pragma unroll
;             for (int m = 0; m < 4; ++m) { const int rl = rl0 + ai * HALF + m * 16; const size_t ro = (size_t)(u.pm * BM + rl) * DM; const float r = rsv[rl];
; #pragma unroll
;                 for (int bj = 0; bj < 2; ++bj) { const int c = cb + bj * HALF; const f32x4 v0 = acc[ai][bj][m][0], v1 = acc[ai][bj][m][1];
;                     if (MODE == 0) { st_bf16x8(X1 + ro + c, v0, v1); st_bf16x8(H + ro + c, v0 * r * gs[bj][0] + sh[bj][0], v1 * r * gs[bj][1] + sh[bj][1]); }
;                     else { *(f32x4*)(out + ro + c) = v0 * r * gs[bj][0]; *(f32x4*)(out + ro + c + 4) = v1 * r * gs[bj][1]; } } }
	v_cndmask_b32_dpp v133, v97, v101, vcc quad_perm:[1,0,3,2] row_mask:0xf bank_mask:0xf
	v_cndmask_b32_dpp v134, v98, v102, vcc quad_perm:[1,0,3,2] row_mask:0xf bank_mask:0xf
	v_cndmask_b32_dpp v135, v99, v103, vcc quad_perm:[1,0,3,2] row_mask:0xf bank_mask:0xf
	s_mov_b64 vcc, s[10:11]
	v_cndmask_b32_dpp v136, v100, v96, vcc quad_perm:[1,0,3,2] row_mask:0xf bank_mask:0xf
	v_cndmask_b32_dpp v137, v101, v97, vcc quad_perm:[1,0,3,2] row_mask:0xf bank_mask:0xf
	v_cndmask_b32_dpp v138, v102, v98, vcc quad_perm:[1,0,3,2] row_mask:0xf bank_mask:0xf
	v_cndmask_b32_dpp v139, v103, v99, vcc quad_perm:[1,0,3,2] row_mask:0xf bank_mask:0xf
	global_store_dwordx4 v[140:141], v[132:135], off offset:-1536
	global_store_dwordx4 v[140:141], v[136:139], off offset:2560
	v_lshl_add_u64 v[140:141], v[140:141], 0, s[12:13]
	v_mov_b32_e32 v198, v188
	v_pk_mul_f32 v[152:153], v[152:153], v[198:199] op_sel_hi:[1,0]
	v_pk_mul_f32 v[94:95], v[94:95], v[198:199] op_sel_hi:[1,0]
	v_pk_mul_f32 v[154:155], v[154:155], v[198:199] op_sel_hi:[1,0]
	v_pk_mul_f32 v[92:93], v[92:93], v[198:199] op_sel_hi:[1,0]
	v_pk_mul_f32 v[152:153], v[12:13], v[152:153]
	v_pk_mul_f32 v[94:95], v[14:15], v[94:95]
	v_pk_mul_f32 v[154:155], v[8:9], v[154:155]
	v_pk_mul_f32 v[92:93], v[10:11], v[92:93]
	s_mov_b64 vcc, s[8:9]
	s_nop 0
	v_cndmask_b32_dpp v132, v154, v152, vcc quad_perm:[1,0,3,2] row_mask:0xf bank_mask:0xf
	v_cndmask_b32_dpp v133, v155, v153, vcc quad_perm:[1,0,3,2] row_mask:0xf bank_mask:0xf
	v_cndmask_b32_dpp v134, v92, v94, vcc quad_perm:[1,0,3,2] row_mask:0xf bank_mask:0xf
	v_cndmask_b32_dpp v135, v93, v95, vcc quad_perm:[1,0,3,2] row_mask:0xf bank_mask:0xf
	s_mov_b64 vcc, s[10:11]
	v_cndmask_b32_dpp v136, v152, v154, vcc quad_perm:[1,0,3,2] row_mask:0xf bank_mask:0xf
	v_cndmask_b32_dpp v137, v153, v155, vcc quad_perm:[1,0,3,2] row_mask:0xf bank_mask:0xf
	v_cndmask_b32_dpp v138, v94, v92, vcc quad_perm:[1,0,3,2] row_mask:0xf bank_mask:0xf
	v_cndmask_b32_dpp v139, v95, v93, vcc quad_perm:[1,0,3,2] row_mask:0xf bank_mask:0xf
	global_store_dwordx4 v[140:141], v[132:135], off offset:-2048
	global_store_dwordx4 v[140:141], v[136:139], off offset:2048
	v_pk_mul_f32 v[158:159], v[158:159], v[198:199] op_sel_hi:[1,0]
	v_pk_mul_f32 v[156:157], v[156:157], v[198:199] op_sel_hi:[1,0]
	v_pk_mul_f32 v[162:163], v[162:163], v[198:199] op_sel_hi:[1,0]
	v_pk_mul_f32 v[160:161], v[160:161], v[198:199] op_sel_hi:[1,0]
	v_pk_mul_f32 v[158:159], v[4:5], v[158:159]
	v_pk_mul_f32 v[156:157], v[6:7], v[156:157]
	v_pk_mul_f32 v[162:163], v[0:1], v[162:163]
	v_pk_mul_f32 v[160:161], v[2:3], v[160:161]
	s_mov_b64 vcc, s[8:9]
	s_nop 0
	v_cndmask_b32_dpp v132, v162, v158, vcc quad_perm:[1,0,3,2] row_mask:0xf bank_mask:0xf
	v_cndmask_b32_dpp v133, v163, v159, vcc quad_perm:[1,0,3,2] row_mask:0xf bank_mask:0xf
	v_cndmask_b32_dpp v134, v160, v156, vcc quad_perm:[1,0,3,2] row_mask:0xf bank_mask:0xf
	v_cndmask_b32_dpp v135, v161, v157, vcc quad_perm:[1,0,3,2] row_mask:0xf bank_mask:0xf
	s_mov_b64 vcc, s[10:11]
	v_cndmask_b32_dpp v136, v158, v162, vcc quad_perm:[1,0,3,2] row_mask:0xf bank_mask:0xf
	v_cndmask_b32_dpp v137, v159, v163, vcc quad_perm:[1,0,3,2] row_mask:0xf bank_mask:0xf
	v_cndmask_b32_dpp v138, v156, v160, vcc quad_perm:[1,0,3,2] row_mask:0xf bank_mask:0xf
	v_cndmask_b32_dpp v139, v157, v161, vcc quad_perm:[1,0,3,2] row_mask:0xf bank_mask:0xf
	global_store_dwordx4 v[140:141], v[132:135], off offset:-1536
	global_store_dwordx4 v[140:141], v[136:139], off offset:2560
	v_lshl_add_u64 v[140:141], v[140:141], 0, s[12:13]
	v_mov_b32_e32 v198, v189
	v_pk_mul_f32 v[166:167], v[166:167], v[198:199] op_sel_hi:[1,0]
	v_pk_mul_f32 v[146:147], v[146:147], v[198:199] op_sel_hi:[1,0]
	v_pk_mul_f32 v[174:175], v[174:175], v[198:199] op_sel_hi:[1,0]
	v_pk_mul_f32 v[148:149], v[148:149], v[198:199] op_sel_hi:[1,0]
	v_pk_mul_f32 v[166:167], v[12:13], v[166:167]
	v_pk_mul_f32 v[146:147], v[14:15], v[146:147]
	v_pk_mul_f32 v[174:175], v[8:9], v[174:175]
	v_pk_mul_f32 v[148:149], v[10:11], v[148:149]
	s_mov_b64 vcc, s[8:9]
	s_nop 0
	v_cndmask_b32_dpp v132, v174, v166, vcc quad_perm:[1,0,3,2] row_mask:0xf bank_mask:0xf
	v_cndmask_b32_dpp v133, v175, v167, vcc quad_perm:[1,0,3,2] row_mask:0xf bank_mask:0xf
	v_cndmask_b32_dpp v134, v148, v146, vcc quad_perm:[1,0,3,2] row_mask:0xf bank_mask:0xf
	v_cndmask_b32_dpp v135, v149, v147, vcc quad_perm:[1,0,3,2] row_mask:0xf bank_mask:0xf
	s_mov_b64 vcc, s[10:11]
	v_cndmask_b32_dpp v136, v166, v174, vcc quad_perm:[1,0,3,2] row_mask:0xf bank_mask:0xf
	v_cndmask_b32_dpp v137, v167, v175, vcc quad_perm:[1,0,3,2] row_mask:0xf bank_mask:0xf
	v_cndmask_b32_dpp v138, v146, v148, vcc quad_perm:[1,0,3,2] row_mask:0xf bank_mask:0xf
	v_cndmask_b32_dpp v139, v147, v149, vcc quad_perm:[1,0,3,2] row_mask:0xf bank_mask:0xf
	global_store_dwordx4 v[140:141], v[132:135], off offset:-2048
	global_store_dwordx4 v[140:141], v[136:139], off offset:2048
	v_pk_mul_f32 v[176:177], v[176:177], v[198:199] op_sel_hi:[1,0]
	v_pk_mul_f32 v[164:165], v[164:165], v[198:199] op_sel_hi:[1,0]
	v_pk_mul_f32 v[180:181], v[180:181], v[198:199] op_sel_hi:[1,0]
	v_pk_mul_f32 v[150:151], v[150:151], v[198:199] op_sel_hi:[1,0]
	v_pk_mul_f32 v[176:177], v[4:5], v[176:177]
	v_pk_mul_f32 v[164:165], v[6:7], v[164:165]
	v_pk_mul_f32 v[180:181], v[0:1], v[180:181]
	v_pk_mul_f32 v[150:151], v[2:3], v[150:151]
	s_mov_b64 vcc, s[8:9]
	s_nop 0
	v_cndmask_b32_dpp v132, v180, v176, vcc quad_perm:[1,0,3,2] row_mask:0xf bank_mask:0xf
	v_cndmask_b32_dpp v133, v181, v177, vcc quad_perm:[1,0,3,2] row_mask:0xf bank_mask:0xf
	v_cndmask_b32_dpp v134, v150, v164, vcc quad_perm:[1,0,3,2] row_mask:0xf bank_mask:0xf
; __device__ __forceinline__ void st_bf16x8(bf16_t* p, const f32x4 a, const f32x4 b) { uint4 o; o.x = cvt_pk_bf16(a[0], a[1]); o.y = cvt_pk_bf16(a[2], a[3]); o.z = cvt_pk_bf16(b[0], b[1]); o.w = cvt_pk_bf16(b[2], b[3]); *(uint4*)p = o; }
;     __device__ __forceinline__ void fused(f32x4 (&acc)[2][2][4][2], const Unit& u, int wr, int wc, int fr, int fq, float* smem) const {
;     ...
;         for (int ai = 0; ai < 2; ++ai)
; #pragma unroll
;             for (int m = 0; m < 4; ++m) { const int rl = rl0 + ai * HALF + m * 16; const size_t ro = (size_t)(u.pm * BM + rl) * DM; const float r = rsv[rl];
; #pragma unroll
;                 for (int bj = 0; bj < 2; ++bj) { const int c = cb + bj * HALF; const f32x4 v0 = acc[ai][bj][m][0], v1 = acc[ai][bj][m][1];
;                     if (MODE == 0) { st_bf16x8(X1 + ro + c, v0, v1); st_bf16x8(H + ro + c, v0 * r * gs[bj][0] + sh[bj][0], v1 * r * gs[bj][1] + sh[bj][1]); }
;                     else { *(f32x4*)(out + ro + c) = v0 * r * gs[bj][0]; *(f32x4*)(out + ro + c + 4) = v1 * r * gs[bj][1]; } } }
	v_cndmask_b32_dpp v135, v151, v165, vcc quad_perm:[1,0,3,2] row_mask:0xf bank_mask:0xf
	s_mov_b64 vcc, s[10:11]
	v_cndmask_b32_dpp v136, v176, v180, vcc quad_perm:[1,0,3,2] row_mask:0xf bank_mask:0xf
	v_cndmask_b32_dpp v137, v177, v181, vcc quad_perm:[1,0,3,2] row_mask:0xf bank_mask:0xf
	v_cndmask_b32_dpp v138, v164, v150, vcc quad_perm:[1,0,3,2] row_mask:0xf bank_mask:0xf
	v_cndmask_b32_dpp v139, v165, v151, vcc quad_perm:[1,0,3,2] row_mask:0xf bank_mask:0xf
	global_store_dwordx4 v[140:141], v[132:135], off offset:-1536
	global_store_dwordx4 v[140:141], v[136:139], off offset:2560
	v_lshl_add_u64 v[140:141], v[140:141], 0, s[14:15]
	v_mov_b32_e32 v198, v190
	v_pk_mul_f32 v[60:61], v[60:61], v[198:199] op_sel_hi:[1,0]
	v_pk_mul_f32 v[62:63], v[62:63], v[198:199] op_sel_hi:[1,0]
	v_pk_mul_f32 v[56:57], v[56:57], v[198:199] op_sel_hi:[1,0]
	v_pk_mul_f32 v[58:59], v[58:59], v[198:199] op_sel_hi:[1,0]
	v_pk_mul_f32 v[60:61], v[12:13], v[60:61]
	v_pk_mul_f32 v[62:63], v[14:15], v[62:63]
	v_pk_mul_f32 v[56:57], v[8:9], v[56:57]
	v_pk_mul_f32 v[58:59], v[10:11], v[58:59]
	s_mov_b64 vcc, s[8:9]
	s_nop 0
	v_cndmask_b32_dpp v132, v56, v60, vcc quad_perm:[1,0,3,2] row_mask:0xf bank_mask:0xf
	v_cndmask_b32_dpp v133, v57, v61, vcc quad_perm:[1,0,3,2] row_mask:0xf bank_mask:0xf
	v_cndmask_b32_dpp v134, v58, v62, vcc quad_perm:[1,0,3,2] row_mask:0xf bank_mask:0xf
	v_cndmask_b32_dpp v135, v59, v63, vcc quad_perm:[1,0,3,2] row_mask:0xf bank_mask:0xf
	s_mov_b64 vcc, s[10:11]
	v_cndmask_b32_dpp v136, v60, v56, vcc quad_perm:[1,0,3,2] row_mask:0xf bank_mask:0xf
	v_cndmask_b32_dpp v137, v61, v57, vcc quad_perm:[1,0,3,2] row_mask:0xf bank_mask:0xf
	v_cndmask_b32_dpp v138, v62, v58, vcc quad_perm:[1,0,3,2] row_mask:0xf bank_mask:0xf
	v_cndmask_b32_dpp v139, v63, v59, vcc quad_perm:[1,0,3,2] row_mask:0xf bank_mask:0xf
	global_store_dwordx4 v[140:141], v[132:135], off offset:-2048 sc1
	global_store_dwordx4 v[140:141], v[136:139], off offset:2048 sc1
	v_pk_mul_f32 v[52:53], v[52:53], v[198:199] op_sel_hi:[1,0]
	v_pk_mul_f32 v[54:55], v[54:55], v[198:199] op_sel_hi:[1,0]
	v_pk_mul_f32 v[48:49], v[48:49], v[198:199] op_sel_hi:[1,0]
	v_pk_mul_f32 v[50:51], v[50:51], v[198:199] op_sel_hi:[1,0]
	v_pk_mul_f32 v[52:53], v[4:5], v[52:53]
	v_pk_mul_f32 v[54:55], v[6:7], v[54:55]
	v_pk_mul_f32 v[48:49], v[0:1], v[48:49]
	v_pk_mul_f32 v[50:51], v[2:3], v[50:51]
	s_mov_b64 vcc, s[8:9]
	s_nop 0
	v_cndmask_b32_dpp v132, v48, v52, vcc quad_perm:[1,0,3,2] row_mask:0xf bank_mask:0xf
	v_cndmask_b32_dpp v133, v49, v53, vcc quad_perm:[1,0,3,2] row_mask:0xf bank_mask:0xf
	v_cndmask_b32_dpp v134, v50, v54, vcc quad_perm:[1,0,3,2] row_mask:0xf bank_mask:0xf
	v_cndmask_b32_dpp v135, v51, v55, vcc quad_perm:[1,0,3,2] row_mask:0xf bank_mask:0xf
	s_mov_b64 vcc, s[10:11]
	v_cndmask_b32_dpp v136, v52, v48, vcc quad_perm:[1,0,3,2] row_mask:0xf bank_mask:0xf
	v_cndmask_b32_dpp v137, v53, v49, vcc quad_perm:[1,0,3,2] row_mask:0xf bank_mask:0xf
	v_cndmask_b32_dpp v138, v54, v50, vcc quad_perm:[1,0,3,2] row_mask:0xf bank_mask:0xf
	v_cndmask_b32_dpp v139, v55, v51, vcc quad_perm:[1,0,3,2] row_mask:0xf bank_mask:0xf
	global_store_dwordx4 v[140:141], v[132:135], off offset:-1536 sc1
	global_store_dwordx4 v[140:141], v[136:139], off offset:2560 sc1
	v_lshl_add_u64 v[140:141], v[140:141], 0, s[12:13]
	v_mov_b32_e32 v198, v191
	v_pk_mul_f32 v[44:45], v[44:45], v[198:199] op_sel_hi:[1,0]
	v_pk_mul_f32 v[46:47], v[46:47], v[198:199] op_sel_hi:[1,0]
	v_pk_mul_f32 v[40:41], v[40:41], v[198:199] op_sel_hi:[1,0]
	v_pk_mul_f32 v[42:43], v[42:43], v[198:199] op_sel_hi:[1,0]
	v_pk_mul_f32 v[44:45], v[12:13], v[44:45]
	v_pk_mul_f32 v[46:47], v[14:15], v[46:47]
	v_pk_mul_f32 v[40:41], v[8:9], v[40:41]
	v_pk_mul_f32 v[42:43], v[10:11], v[42:43]
	s_mov_b64 vcc, s[8:9]
	s_nop 0
	v_cndmask_b32_dpp v132, v40, v44, vcc quad_perm:[1,0,3,2] row_mask:0xf bank_mask:0xf
	v_cndmask_b32_dpp v133, v41, v45, vcc quad_perm:[1,0,3,2] row_mask:0xf bank_mask:0xf
	v_cndmask_b32_dpp v134, v42, v46, vcc quad_perm:[1,0,3,2] row_mask:0xf bank_mask:0xf
	v_cndmask_b32_dpp v135, v43, v47, vcc quad_perm:[1,0,3,2] row_mask:0xf bank_mask:0xf
	s_mov_b64 vcc, s[10:11]
	v_cndmask_b32_dpp v136, v44, v40, vcc quad_perm:[1,0,3,2] row_mask:0xf bank_mask:0xf
	v_cndmask_b32_dpp v137, v45, v41, vcc quad_perm:[1,0,3,2] row_mask:0xf bank_mask:0xf
	v_cndmask_b32_dpp v138, v46, v42, vcc quad_perm:[1,0,3,2] row_mask:0xf bank_mask:0xf
	v_cndmask_b32_dpp v139, v47, v43, vcc quad_perm:[1,0,3,2] row_mask:0xf bank_mask:0xf
	global_store_dwordx4 v[140:141], v[132:135], off offset:-2048 sc1
	global_store_dwordx4 v[140:141], v[136:139], off offset:2048 sc1
	v_pk_mul_f32 v[36:37], v[36:37], v[198:199] op_sel_hi:[1,0]
	v_pk_mul_f32 v[38:39], v[38:39], v[198:199] op_sel_hi:[1,0]
	v_pk_mul_f32 v[32:33], v[32:33], v[198:199] op_sel_hi:[1,0]
	v_pk_mul_f32 v[34:35], v[34:35], v[198:199] op_sel_hi:[1,0]
	v_pk_mul_f32 v[36:37], v[4:5], v[36:37]
	v_pk_mul_f32 v[38:39], v[6:7], v[38:39]
	v_pk_mul_f32 v[32:33], v[0:1], v[32:33]
	v_pk_mul_f32 v[34:35], v[2:3], v[34:35]
	s_mov_b64 vcc, s[8:9]
	s_nop 0
	v_cndmask_b32_dpp v132, v32, v36, vcc quad_perm:[1,0,3,2] row_mask:0xf bank_mask:0xf
	v_cndmask_b32_dpp v133, v33, v37, vcc quad_perm:[1,0,3,2] row_mask:0xf bank_mask:0xf
	v_cndmask_b32_dpp v134, v34, v38, vcc quad_perm:[1,0,3,2] row_mask:0xf bank_mask:0xf
	v_cndmask_b32_dpp v135, v35, v39, vcc quad_perm:[1,0,3,2] row_mask:0xf bank_mask:0xf
	s_mov_b64 vcc, s[10:11]
	v_cndmask_b32_dpp v136, v36, v32, vcc quad_perm:[1,0,3,2] row_mask:0xf bank_mask:0xf
	v_cndmask_b32_dpp v137, v37, v33, vcc quad_perm:[1,0,3,2] row_mask:0xf bank_mask:0xf
; __device__ __forceinline__ void st_bf16x8(bf16_t* p, const f32x4 a, const f32x4 b) { uint4 o; o.x = cvt_pk_bf16(a[0], a[1]); o.y = cvt_pk_bf16(a[2], a[3]); o.z = cvt_pk_bf16(b[0], b[1]); o.w = cvt_pk_bf16(b[2], b[3]); *(uint4*)p = o; }
;     __device__ __forceinline__ void fused(f32x4 (&acc)[2][2][4][2], const Unit& u, int wr, int wc, int fr, int fq, float* smem) const {
;     ...
;         for (int ai = 0; ai < 2; ++ai)
; #pragma unroll
;             for (int m = 0; m < 4; ++m) { const int rl = rl0 + ai * HALF + m * 16; const size_t ro = (size_t)(u.pm * BM + rl) * DM; const float r = rsv[rl];
; #pragma unroll
;                 for (int bj = 0; bj < 2; ++bj) { const int c = cb + bj * HALF; const f32x4 v0 = acc[ai][bj][m][0], v1 = acc[ai][bj][m][1];
;                     if (MODE == 0) { st_bf16x8(X1 + ro + c, v0, v1); st_bf16x8(H + ro + c, v0 * r * gs[bj][0] + sh[bj][0], v1 * r * gs[bj][1] + sh[bj][1]); }
;                     else { *(f32x4*)(out + ro + c) = v0 * r * gs[bj][0]; *(f32x4*)(out + ro + c + 4) = v1 * r * gs[bj][1]; } } }
;         __syncthreads();
	v_cndmask_b32_dpp v138, v38, v34, vcc quad_perm:[1,0,3,2] row_mask:0xf bank_mask:0xf
	v_cndmask_b32_dpp v139, v39, v35, vcc quad_perm:[1,0,3,2] row_mask:0xf bank_mask:0xf
	global_store_dwordx4 v[140:141], v[132:135], off offset:-1536 sc1
	global_store_dwordx4 v[140:141], v[136:139], off offset:2560 sc1
	v_lshl_add_u64 v[140:141], v[140:141], 0, s[12:13]
	v_mov_b32_e32 v198, v192
	v_pk_mul_f32 v[28:29], v[28:29], v[198:199] op_sel_hi:[1,0]
	v_pk_mul_f32 v[30:31], v[30:31], v[198:199] op_sel_hi:[1,0]
	v_pk_mul_f32 v[24:25], v[24:25], v[198:199] op_sel_hi:[1,0]
	v_pk_mul_f32 v[26:27], v[26:27], v[198:199] op_sel_hi:[1,0]
	v_pk_mul_f32 v[28:29], v[12:13], v[28:29]
	v_pk_mul_f32 v[30:31], v[14:15], v[30:31]
	v_pk_mul_f32 v[24:25], v[8:9], v[24:25]
	v_pk_mul_f32 v[26:27], v[10:11], v[26:27]
	s_mov_b64 vcc, s[8:9]
	s_nop 0
	v_cndmask_b32_dpp v132, v24, v28, vcc quad_perm:[1,0,3,2] row_mask:0xf bank_mask:0xf
	v_cndmask_b32_dpp v133, v25, v29, vcc quad_perm:[1,0,3,2] row_mask:0xf bank_mask:0xf
	v_cndmask_b32_dpp v134, v26, v30, vcc quad_perm:[1,0,3,2] row_mask:0xf bank_mask:0xf
	v_cndmask_b32_dpp v135, v27, v31, vcc quad_perm:[1,0,3,2] row_mask:0xf bank_mask:0xf
	s_mov_b64 vcc, s[10:11]
	v_cndmask_b32_dpp v136, v28, v24, vcc quad_perm:[1,0,3,2] row_mask:0xf bank_mask:0xf
	v_cndmask_b32_dpp v137, v29, v25, vcc quad_perm:[1,0,3,2] row_mask:0xf bank_mask:0xf
	v_cndmask_b32_dpp v138, v30, v26, vcc quad_perm:[1,0,3,2] row_mask:0xf bank_mask:0xf
	v_cndmask_b32_dpp v139, v31, v27, vcc quad_perm:[1,0,3,2] row_mask:0xf bank_mask:0xf
	global_store_dwordx4 v[140:141], v[132:135], off offset:-2048 sc1
	global_store_dwordx4 v[140:141], v[136:139], off offset:2048 sc1
	v_pk_mul_f32 v[20:21], v[20:21], v[198:199] op_sel_hi:[1,0]
	v_pk_mul_f32 v[22:23], v[22:23], v[198:199] op_sel_hi:[1,0]
	v_pk_mul_f32 v[16:17], v[16:17], v[198:199] op_sel_hi:[1,0]
	v_pk_mul_f32 v[18:19], v[18:19], v[198:199] op_sel_hi:[1,0]
	v_pk_mul_f32 v[20:21], v[4:5], v[20:21]
	v_pk_mul_f32 v[22:23], v[6:7], v[22:23]
	v_pk_mul_f32 v[16:17], v[0:1], v[16:17]
	v_pk_mul_f32 v[18:19], v[2:3], v[18:19]
	s_mov_b64 vcc, s[8:9]
	s_nop 0
	v_cndmask_b32_dpp v132, v16, v20, vcc quad_perm:[1,0,3,2] row_mask:0xf bank_mask:0xf
	v_cndmask_b32_dpp v133, v17, v21, vcc quad_perm:[1,0,3,2] row_mask:0xf bank_mask:0xf
	v_cndmask_b32_dpp v134, v18, v22, vcc quad_perm:[1,0,3,2] row_mask:0xf bank_mask:0xf
	v_cndmask_b32_dpp v135, v19, v23, vcc quad_perm:[1,0,3,2] row_mask:0xf bank_mask:0xf
	s_mov_b64 vcc, s[10:11]
	v_cndmask_b32_dpp v136, v20, v16, vcc quad_perm:[1,0,3,2] row_mask:0xf bank_mask:0xf
	v_cndmask_b32_dpp v137, v21, v17, vcc quad_perm:[1,0,3,2] row_mask:0xf bank_mask:0xf
	v_cndmask_b32_dpp v138, v22, v18, vcc quad_perm:[1,0,3,2] row_mask:0xf bank_mask:0xf
	v_cndmask_b32_dpp v139, v23, v19, vcc quad_perm:[1,0,3,2] row_mask:0xf bank_mask:0xf
	global_store_dwordx4 v[140:141], v[132:135], off offset:-1536 sc1
	global_store_dwordx4 v[140:141], v[136:139], off offset:2560 sc1
	v_lshl_add_u64 v[140:141], v[140:141], 0, s[12:13]
	v_mov_b32_e32 v198, v193
	v_pk_mul_f32 v[70:71], v[70:71], v[198:199] op_sel_hi:[1,0]
	v_pk_mul_f32 v[64:65], v[64:65], v[198:199] op_sel_hi:[1,0]
	v_pk_mul_f32 v[72:73], v[72:73], v[198:199] op_sel_hi:[1,0]
	v_pk_mul_f32 v[66:67], v[66:67], v[198:199] op_sel_hi:[1,0]
	v_pk_mul_f32 v[70:71], v[12:13], v[70:71]
	v_pk_mul_f32 v[64:65], v[14:15], v[64:65]
	v_pk_mul_f32 v[72:73], v[8:9], v[72:73]
	v_pk_mul_f32 v[66:67], v[10:11], v[66:67]
	s_mov_b64 vcc, s[8:9]
	s_nop 0
	v_cndmask_b32_dpp v132, v72, v70, vcc quad_perm:[1,0,3,2] row_mask:0xf bank_mask:0xf
	v_cndmask_b32_dpp v133, v73, v71, vcc quad_perm:[1,0,3,2] row_mask:0xf bank_mask:0xf
	v_cndmask_b32_dpp v134, v66, v64, vcc quad_perm:[1,0,3,2] row_mask:0xf bank_mask:0xf
	v_cndmask_b32_dpp v135, v67, v65, vcc quad_perm:[1,0,3,2] row_mask:0xf bank_mask:0xf
	s_mov_b64 vcc, s[10:11]
	v_cndmask_b32_dpp v136, v70, v72, vcc quad_perm:[1,0,3,2] row_mask:0xf bank_mask:0xf
	v_cndmask_b32_dpp v137, v71, v73, vcc quad_perm:[1,0,3,2] row_mask:0xf bank_mask:0xf
	v_cndmask_b32_dpp v138, v64, v66, vcc quad_perm:[1,0,3,2] row_mask:0xf bank_mask:0xf
	v_cndmask_b32_dpp v139, v65, v67, vcc quad_perm:[1,0,3,2] row_mask:0xf bank_mask:0xf
	global_store_dwordx4 v[140:141], v[132:135], off offset:-2048 sc1
	global_store_dwordx4 v[140:141], v[136:139], off offset:2048 sc1
	v_pk_mul_f32 v[76:77], v[76:77], v[198:199] op_sel_hi:[1,0]
	v_pk_mul_f32 v[68:69], v[68:69], v[198:199] op_sel_hi:[1,0]
	v_pk_mul_f32 v[78:79], v[78:79], v[198:199] op_sel_hi:[1,0]
	v_pk_mul_f32 v[74:75], v[74:75], v[198:199] op_sel_hi:[1,0]
	v_pk_mul_f32 v[76:77], v[4:5], v[76:77]
	v_pk_mul_f32 v[68:69], v[6:7], v[68:69]
	v_pk_mul_f32 v[78:79], v[0:1], v[78:79]
	v_pk_mul_f32 v[74:75], v[2:3], v[74:75]
	s_mov_b64 vcc, s[8:9]
	s_nop 0
	v_cndmask_b32_dpp v132, v78, v76, vcc quad_perm:[1,0,3,2] row_mask:0xf bank_mask:0xf
	v_cndmask_b32_dpp v133, v79, v77, vcc quad_perm:[1,0,3,2] row_mask:0xf bank_mask:0xf
	v_cndmask_b32_dpp v134, v74, v68, vcc quad_perm:[1,0,3,2] row_mask:0xf bank_mask:0xf
	v_cndmask_b32_dpp v135, v75, v69, vcc quad_perm:[1,0,3,2] row_mask:0xf bank_mask:0xf
	s_mov_b64 vcc, s[10:11]
	v_cndmask_b32_dpp v136, v76, v78, vcc quad_perm:[1,0,3,2] row_mask:0xf bank_mask:0xf
	v_cndmask_b32_dpp v137, v77, v79, vcc quad_perm:[1,0,3,2] row_mask:0xf bank_mask:0xf
	v_cndmask_b32_dpp v138, v68, v74, vcc quad_perm:[1,0,3,2] row_mask:0xf bank_mask:0xf
	v_cndmask_b32_dpp v139, v69, v75, vcc quad_perm:[1,0,3,2] row_mask:0xf bank_mask:0xf
	global_store_dwordx4 v[140:141], v[132:135], off offset:-1536 sc1
	global_store_dwordx4 v[140:141], v[136:139], off offset:2560 sc1
	s_barrier
